# instruction selection: accumulator zero-init with 64 v_mov_b64 instead of 128 v_mov_b32 per unit (gate/up and w_in phases)
# baseline (speedup 1.0000x reference)
;     __host__ __device__ bool next(int i, Unit& u) const { if (i != 0 || c < 0 || c >= n) return false; u.pm = c / nN; u.pn = c - u.pm * nN; return true; }
; template <class Epi, class Sched, bool ALIGN_EPI, bool SP2, int KK, int LDA, int APN>
; __device__ __forceinline__ void gemm_phase(PG8_LAS unsigned char* lds, const Gemm g, const Sched& S, const Epi& E, const int wid) {
;     ...
;         const bool has_next = S.next(ui + 1, nxt);
;         const char* nA = has_next ? (const char*)g.A + (size_t)nxt.pm * tstepA + (size_t)nxt.pn * APN : cA; const char* nB = has_next ? (const char*)g.Bt + (size_t)nxt.pn * tstep : cB;
;     ...
; #pragma unroll
;         for (int a = 0; a < 2; ++a)
; #pragma unroll
;             for (int b = 0; b < 2; ++b)
; #pragma unroll
;                 for (int m = 0; m < 4; ++m)
; #pragma unroll
;                     for (int n = 0; n < 2; ++n) acc[a][b][m][n] = (f32x4){0.f, 0.f, 0.f, 0.f};
.LBB0_219:
	s_ashr_i32 s37, s36, 31
	s_lshl_b64 s[38:39], s[36:37], 20
	s_add_u32 s38, s49, s38
	s_addc_u32 s39, s50, s39
	s_and_b64 s[42:43], s[0:1], exec
	s_cselect_b32 s37, s39, s45
	s_cselect_b32 s60, s38, s44
	s_ashr_i32 s27, s26, 31
	s_lshl_b64 s[42:43], s[26:27], 20
	s_add_u32 s42, s10, s42
	s_addc_u32 s43, s11, s43
	s_and_b64 s[46:47], s[0:1], exec
	s_cselect_b32 s27, s43, s31
	s_cselect_b32 s61, s42, s30
	s_add_u32 s64, s30, 0x100
	s_addc_u32 s65, s31, 0
	s_add_u32 s30, s44, 0x80080
	v_mov_b64_e32 v[0:1], 0
	v_mov_b64_e32 v[2:3], 0
	v_mov_b64_e32 v[4:5], 0
	v_mov_b64_e32 v[6:7], 0
	v_mov_b64_e32 v[8:9], 0
	v_mov_b64_e32 v[10:11], 0
	v_mov_b64_e32 v[12:13], 0
	v_mov_b64_e32 v[14:15], 0
	v_mov_b64_e32 v[16:17], 0
	v_mov_b64_e32 v[18:19], 0
	v_mov_b64_e32 v[20:21], 0
	v_mov_b64_e32 v[22:23], 0
	v_mov_b64_e32 v[24:25], 0
	v_mov_b64_e32 v[26:27], 0
	v_mov_b64_e32 v[28:29], 0
	v_mov_b64_e32 v[30:31], 0
	v_mov_b64_e32 v[32:33], 0
	v_mov_b64_e32 v[34:35], 0
	v_mov_b64_e32 v[36:37], 0
	v_mov_b64_e32 v[38:39], 0
	v_mov_b64_e32 v[40:41], 0
	v_mov_b64_e32 v[42:43], 0
	v_mov_b64_e32 v[44:45], 0
	v_mov_b64_e32 v[46:47], 0
	v_mov_b64_e32 v[48:49], 0
	v_mov_b64_e32 v[50:51], 0
	v_mov_b64_e32 v[52:53], 0
	v_mov_b64_e32 v[54:55], 0
	v_mov_b64_e32 v[56:57], 0
	v_mov_b64_e32 v[58:59], 0
	v_mov_b64_e32 v[60:61], 0
	v_mov_b64_e32 v[62:63], 0
	v_mov_b64_e32 v[64:65], 0
	v_mov_b64_e32 v[66:67], 0
	v_mov_b64_e32 v[68:69], 0
	v_mov_b64_e32 v[70:71], 0
	v_mov_b64_e32 v[72:73], 0
	v_mov_b64_e32 v[74:75], 0
	v_mov_b64_e32 v[76:77], 0
	v_mov_b64_e32 v[78:79], 0
	v_mov_b64_e32 v[80:81], 0
	v_mov_b64_e32 v[82:83], 0
	v_mov_b64_e32 v[84:85], 0
	v_mov_b64_e32 v[86:87], 0
	v_mov_b64_e32 v[88:89], 0
	v_mov_b64_e32 v[90:91], 0
	v_mov_b64_e32 v[92:93], 0
	v_mov_b64_e32 v[94:95], 0
	v_mov_b64_e32 v[98:99], 0
	v_mov_b64_e32 v[100:101], 0
	v_mov_b64_e32 v[102:103], 0
	v_mov_b64_e32 v[104:105], 0
	v_mov_b64_e32 v[106:107], 0
	v_mov_b64_e32 v[108:109], 0
	v_mov_b64_e32 v[110:111], 0
	v_mov_b64_e32 v[112:113], 0
	v_mov_b64_e32 v[114:115], 0
	v_mov_b64_e32 v[116:117], 0
	v_mov_b64_e32 v[118:119], 0
	v_mov_b64_e32 v[120:121], 0
	v_mov_b64_e32 v[122:123], 0
	v_mov_b64_e32 v[124:125], 0
	v_mov_b64_e32 v[126:127], 0
	v_mov_b64_e32 v[128:129], 0
	s_addc_u32 s31, s45, 0
	s_mov_b32 s66, -2

;     __host__ __device__ bool next(int i, Unit& u) const { if (i != 0 || c < 0 || c >= n) return false; u.pm = c / nN; u.pn = c - u.pm * nN; return true; }
; template <class Epi, class Sched, bool ALIGN_EPI, bool SP2, int KK, int LDA, int APN>
; __device__ __forceinline__ void gemm_phase(PG8_LAS unsigned char* lds, const Gemm g, const Sched& S, const Epi& E, const int wid) {
;     ...
;         const bool has_next = S.next(ui + 1, nxt);
;         const char* nA = has_next ? (const char*)g.A + (size_t)nxt.pm * tstepA + (size_t)nxt.pn * APN : cA; const char* nB = has_next ? (const char*)g.Bt + (size_t)nxt.pn * tstep : cB;
;     ...
; #pragma unroll
;         for (int a = 0; a < 2; ++a)
; #pragma unroll
;             for (int b = 0; b < 2; ++b)
; #pragma unroll
;                 for (int m = 0; m < 4; ++m)
; #pragma unroll
;                     for (int n = 0; n < 2; ++n) acc[a][b][m][n] = (f32x4){0.f, 0.f, 0.f, 0.f};
.LBB0_405:
	s_ashr_i32 s59, s58, 31
	s_lshl_b64 s[6:7], s[58:59], 20
	s_add_u32 s60, s30, s6
	s_addc_u32 s61, s31, s7
	s_and_b64 s[6:7], s[38:39], exec
	s_cselect_b32 s3, s61, s19
	s_cselect_b32 s6, s60, s18
	s_ashr_i32 s55, s54, 31
	s_lshl_b64 s[8:9], s[54:55], 20
	s_add_u32 s66, s40, s8
	s_addc_u32 s67, s41, s9
	s_and_b64 s[8:9], s[38:39], exec
	s_cselect_b32 s7, s67, s17
	s_cselect_b32 s8, s66, s16
	s_add_u32 s9, s16, 0x100
	s_addc_u32 s10, s17, 0
	s_add_u32 s16, s18, 0x80080
	v_mov_b64_e32 v[0:1], 0
	v_mov_b64_e32 v[2:3], 0
	v_mov_b64_e32 v[4:5], 0
	v_mov_b64_e32 v[6:7], 0
	v_mov_b64_e32 v[8:9], 0
	v_mov_b64_e32 v[10:11], 0
	v_mov_b64_e32 v[12:13], 0
	v_mov_b64_e32 v[14:15], 0
	v_mov_b64_e32 v[16:17], 0
	v_mov_b64_e32 v[18:19], 0
	v_mov_b64_e32 v[20:21], 0
	v_mov_b64_e32 v[22:23], 0
	v_mov_b64_e32 v[24:25], 0
	v_mov_b64_e32 v[26:27], 0
	v_mov_b64_e32 v[28:29], 0
	v_mov_b64_e32 v[30:31], 0
	v_mov_b64_e32 v[32:33], 0
	v_mov_b64_e32 v[34:35], 0
	v_mov_b64_e32 v[36:37], 0
	v_mov_b64_e32 v[38:39], 0
	v_mov_b64_e32 v[40:41], 0
	v_mov_b64_e32 v[42:43], 0
	v_mov_b64_e32 v[44:45], 0
	v_mov_b64_e32 v[46:47], 0
	v_mov_b64_e32 v[48:49], 0
	v_mov_b64_e32 v[50:51], 0
	v_mov_b64_e32 v[52:53], 0
	v_mov_b64_e32 v[54:55], 0
	v_mov_b64_e32 v[56:57], 0
	v_mov_b64_e32 v[58:59], 0
	v_mov_b64_e32 v[60:61], 0
	v_mov_b64_e32 v[62:63], 0
	v_mov_b64_e32 v[64:65], 0
	v_mov_b64_e32 v[66:67], 0
	v_mov_b64_e32 v[68:69], 0
	v_mov_b64_e32 v[70:71], 0
	v_mov_b64_e32 v[72:73], 0
	v_mov_b64_e32 v[74:75], 0
	v_mov_b64_e32 v[76:77], 0
	v_mov_b64_e32 v[78:79], 0
	v_mov_b64_e32 v[80:81], 0
	v_mov_b64_e32 v[82:83], 0
	v_mov_b64_e32 v[84:85], 0
	v_mov_b64_e32 v[86:87], 0
	v_mov_b64_e32 v[88:89], 0
	v_mov_b64_e32 v[90:91], 0
	v_mov_b64_e32 v[92:93], 0
	v_mov_b64_e32 v[94:95], 0
	v_mov_b64_e32 v[98:99], 0
	v_mov_b64_e32 v[100:101], 0
	v_mov_b64_e32 v[102:103], 0
	v_mov_b64_e32 v[104:105], 0
	v_mov_b64_e32 v[106:107], 0
	v_mov_b64_e32 v[108:109], 0
	v_mov_b64_e32 v[110:111], 0
	v_mov_b64_e32 v[112:113], 0
	v_mov_b64_e32 v[114:115], 0
	v_mov_b64_e32 v[116:117], 0
	v_mov_b64_e32 v[118:119], 0
	v_mov_b64_e32 v[120:121], 0
	v_mov_b64_e32 v[122:123], 0
	v_mov_b64_e32 v[124:125], 0
	v_mov_b64_e32 v[126:127], 0
	v_mov_b64_e32 v[128:129], 0
	s_addc_u32 s17, s19, 0
	s_mov_b32 s11, -2

;     __host__ __device__ bool next(int i, Unit& u) const { if (i != 0 || c < 0 || c >= n) return false; u.pm = c / nN; u.pn = c - u.pm * nN; return true; }
; template <class Epi, class Sched, bool ALIGN_EPI, bool SP2, int KK, int LDA, int APN>
; __device__ __forceinline__ void gemm_phase(PG8_LAS unsigned char* lds, const Gemm g, const Sched& S, const Epi& E, const int wid) {
;     ...
;         const bool has_next = S.next(ui + 1, nxt);
;         const char* nA = has_next ? (const char*)g.A + (size_t)nxt.pm * tstepA + (size_t)nxt.pn * APN : cA; const char* nB = has_next ? (const char*)g.Bt + (size_t)nxt.pn * tstep : cB;
;     ...
; #pragma unroll
;         for (int a = 0; a < 2; ++a)
; #pragma unroll
;             for (int b = 0; b < 2; ++b)
; #pragma unroll
;                 for (int m = 0; m < 4; ++m)
; #pragma unroll
;                     for (int n = 0; n < 2; ++n) acc[a][b][m][n] = (f32x4){0.f, 0.f, 0.f, 0.f};
.LBB0_778:
	s_ashr_i32 s35, s34, 31
	s_lshl_b64 s[36:37], s[34:35], 20
	s_add_u32 s36, s8, s36
	s_addc_u32 s37, s9, s37
	s_and_b64 s[38:39], s[0:1], exec
	s_cselect_b32 s35, s37, s43
	s_cselect_b32 s51, s36, s42
	s_ashr_i32 s27, s26, 31
	s_lshl_b64 s[38:39], s[26:27], 20
	s_add_u32 s38, s10, s38
	s_addc_u32 s39, s11, s39
	s_and_b64 s[44:45], s[0:1], exec
	s_cselect_b32 s27, s39, s31
	s_cselect_b32 s52, s38, s30
	s_add_u32 s53, s30, 0x100
	s_addc_u32 s54, s31, 0
	s_add_u32 s30, s42, 0x80080
	v_mov_b64_e32 v[0:1], 0
	v_mov_b64_e32 v[2:3], 0
	v_mov_b64_e32 v[4:5], 0
	v_mov_b64_e32 v[6:7], 0
	v_mov_b64_e32 v[8:9], 0
	v_mov_b64_e32 v[10:11], 0
	v_mov_b64_e32 v[12:13], 0
	v_mov_b64_e32 v[14:15], 0
	v_mov_b64_e32 v[16:17], 0
	v_mov_b64_e32 v[18:19], 0
	v_mov_b64_e32 v[20:21], 0
	v_mov_b64_e32 v[22:23], 0
	v_mov_b64_e32 v[24:25], 0
	v_mov_b64_e32 v[26:27], 0
	v_mov_b64_e32 v[28:29], 0
	v_mov_b64_e32 v[30:31], 0
	v_mov_b64_e32 v[32:33], 0
	v_mov_b64_e32 v[34:35], 0
	v_mov_b64_e32 v[36:37], 0
	v_mov_b64_e32 v[38:39], 0
	v_mov_b64_e32 v[40:41], 0
	v_mov_b64_e32 v[42:43], 0
	v_mov_b64_e32 v[44:45], 0
	v_mov_b64_e32 v[46:47], 0
	v_mov_b64_e32 v[48:49], 0
	v_mov_b64_e32 v[50:51], 0
	v_mov_b64_e32 v[52:53], 0
	v_mov_b64_e32 v[54:55], 0
	v_mov_b64_e32 v[56:57], 0
	v_mov_b64_e32 v[58:59], 0
	v_mov_b64_e32 v[60:61], 0
	v_mov_b64_e32 v[62:63], 0
	v_mov_b64_e32 v[64:65], 0
	v_mov_b64_e32 v[66:67], 0
	v_mov_b64_e32 v[68:69], 0
	v_mov_b64_e32 v[70:71], 0
	v_mov_b64_e32 v[72:73], 0
	v_mov_b64_e32 v[74:75], 0
	v_mov_b64_e32 v[76:77], 0
	v_mov_b64_e32 v[78:79], 0
	v_mov_b64_e32 v[80:81], 0
	v_mov_b64_e32 v[82:83], 0
	v_mov_b64_e32 v[84:85], 0
	v_mov_b64_e32 v[86:87], 0
	v_mov_b64_e32 v[88:89], 0
	v_mov_b64_e32 v[90:91], 0
	v_mov_b64_e32 v[92:93], 0
	v_mov_b64_e32 v[94:95], 0
	v_mov_b64_e32 v[98:99], 0
	v_mov_b64_e32 v[100:101], 0
	v_mov_b64_e32 v[102:103], 0
	v_mov_b64_e32 v[104:105], 0
	v_mov_b64_e32 v[106:107], 0
	v_mov_b64_e32 v[108:109], 0
	v_mov_b64_e32 v[110:111], 0
	v_mov_b64_e32 v[112:113], 0
	v_mov_b64_e32 v[114:115], 0
	v_mov_b64_e32 v[116:117], 0
	v_mov_b64_e32 v[118:119], 0
	v_mov_b64_e32 v[120:121], 0
	v_mov_b64_e32 v[122:123], 0
	v_mov_b64_e32 v[124:125], 0
	v_mov_b64_e32 v[126:127], 0
	v_mov_b64_e32 v[128:129], 0
	s_addc_u32 s31, s43, 0
	s_mov_b32 s55, -2
